# prep: x->bf16 conversion stores (full 1 KB lines per wave) made write-through so the first grid barrier has less dirty L2 data to flush
# baseline (speedup 1.0000x reference)
; DI unsigned pk2(float lo, float hi) { const f32x2 v = {lo, hi}; const bf16x2_t b = __builtin_convertvector(v, bf16x2_t); return __builtin_bit_cast(unsigned, b); }
; DI void prep_phase(const Params& p, char* lds) {
;     ...
;         auto conv = [&](const float* __restrict__ srcp, bf16_t* __restrict__ dstp, size_t n8) {
;             for (size_t I = (size_t)bid * NTHR + tid; I < n8; I += (size_t)nb * NTHR) {
;                 const int c8 = (int)(I & 3), row = (int)(I >> 2) & 127, kt = (int)(I >> 9) & 31, blk = (int)(I >> 14);
;                 const float* s = srcp + ((size_t)(blk * 128 + row)) * 1024 + kt * 32 + c8 * 8;
;                 const f32x4 a = *(const f32x4*)s, b = *(const f32x4*)(s + 4);
;                 *(u32x4*)(dstp + I * 8) = (u32x4){pk2(a[0], a[1]), pk2(a[2], a[3]), pk2(b[0], b[1]), pk2(b[2], b[3])};
;             }
;         };
;         conv(p.x, WS_PTR(bf16_t, OFF_XB0), (size_t)T_TOK * DM / 8);
;         conv(p.mem, WS_PTR(bf16_t, OFF_MEMB), (size_t)4096 * DM / 8);
.Lcv_loop:
	s_cmp_lt_u32 s15, 2
	s_cbranch_scc1 .Lcv_single
	v_lshrrev_b32_e32 v1, 2, v12
	v_lshrrev_b32_e32 v10, 7, v12
	v_and_b32_e32 v14, 0x7f, v1
	v_and_or_b32 v10, v10, s12, v14
	v_lshlrev_b32_e32 v10, 12, v10
	v_lshlrev_b32_e32 v16, 3, v12
	v_and_b32_e32 v16, 24, v16
	v_lshl_add_u64 v[14:15], s[52:53], 0, v[10:11]
	v_and_b32_e32 v10, 0xf80, v1
	v_lshl_add_u64 v[14:15], v[14:15], 0, v[10:11]
	v_lshlrev_b32_e32 v10, 2, v16
	v_lshl_add_u64 v[22:23], v[14:15], 0, v[10:11]
	global_load_dwordx4 v[14:17], v[22:23], off
	global_load_dwordx4 v[18:21], v[22:23], off offset:16
	v_lshl_add_u64 v[6:7], v[12:13], 4, s[22:23]
	v_add_u32_e32 v12, 0x20000, v12
	v_lshrrev_b32_e32 v1, 2, v12
	v_lshrrev_b32_e32 v10, 7, v12
	v_and_b32_e32 v216, 0x7f, v1
	v_and_or_b32 v10, v10, s12, v216
	v_lshlrev_b32_e32 v10, 12, v10
	v_lshlrev_b32_e32 v218, 3, v12
	v_and_b32_e32 v218, 24, v218
	v_lshl_add_u64 v[216:217], s[52:53], 0, v[10:11]
	v_and_b32_e32 v10, 0xf80, v1
	v_lshl_add_u64 v[216:217], v[216:217], 0, v[10:11]
	v_lshlrev_b32_e32 v10, 2, v218
	v_lshl_add_u64 v[224:225], v[216:217], 0, v[10:11]
	global_load_dwordx4 v[216:219], v[224:225], off
	global_load_dwordx4 v[220:223], v[224:225], off offset:16
	v_lshl_add_u64 v[8:9], v[12:13], 4, s[22:23]
	v_add_u32_e32 v12, 0x20000, v12
	s_waitcnt vmcnt(3)
	v_cvt_pk_bf16_f32 v14, v14, v15
	v_cvt_pk_bf16_f32 v15, v16, v17
	s_waitcnt vmcnt(2)
	v_cvt_pk_bf16_f32 v16, v18, v19
	v_cvt_pk_bf16_f32 v17, v20, v21
	s_waitcnt vmcnt(1)
	v_cvt_pk_bf16_f32 v216, v216, v217
	v_cvt_pk_bf16_f32 v217, v218, v219
	s_waitcnt vmcnt(0)
	v_cvt_pk_bf16_f32 v218, v220, v221
	v_cvt_pk_bf16_f32 v219, v222, v223
	global_store_dwordx4 v[6:7], v[14:17], off sc1
	global_store_dwordx4 v[8:9], v[216:219], off sc1
	s_sub_u32 s15, s15, 2
	s_cmp_lg_u32 s15, 0
	s_cbranch_scc1 .Lcv_loop
	s_branch .Lcv_next
.Lcv_single:
	v_lshrrev_b32_e32 v1, 2, v12
	v_lshrrev_b32_e32 v10, 7, v12
	v_and_b32_e32 v14, 0x7f, v1
	v_and_or_b32 v10, v10, s12, v14
	v_lshlrev_b32_e32 v10, 12, v10
	v_lshlrev_b32_e32 v16, 3, v12
	v_and_b32_e32 v16, 24, v16
	v_lshl_add_u64 v[14:15], s[52:53], 0, v[10:11]
	v_and_b32_e32 v10, 0xf80, v1
	v_lshl_add_u64 v[14:15], v[14:15], 0, v[10:11]
	v_lshlrev_b32_e32 v10, 2, v16
	v_lshl_add_u64 v[22:23], v[14:15], 0, v[10:11]
	global_load_dwordx4 v[14:17], v[22:23], off
	global_load_dwordx4 v[18:21], v[22:23], off offset:16
	v_lshl_add_u64 v[6:7], v[12:13], 4, s[22:23]
	v_add_u32_e32 v12, 0x20000, v12
	s_waitcnt vmcnt(1)
	v_cvt_pk_bf16_f32 v14, v14, v15
	v_cvt_pk_bf16_f32 v15, v16, v17
	s_waitcnt vmcnt(0)
	v_cvt_pk_bf16_f32 v16, v18, v19
	v_cvt_pk_bf16_f32 v17, v20, v21
	global_store_dwordx4 v[6:7], v[14:17], off sc1
	s_sub_u32 s15, s15, 1
	s_cmp_lg_u32 s15, 0
	s_cbranch_scc1 .Lcv_loop
